# final rmsnorm phase: row loop software-pipelined (next row's loads in flight, counted vmcnt) and the 64-lane sum via DPP + permlane swaps instead of six ds_bpermute round trips
# baseline (speedup 1.0000x reference)
.LBB0_1746:
	global_load_dwordx4 v[26:29], v[16:17], off offset:-3072
	global_load_dwordx4 v[30:33], v[16:17], off offset:-2048
	global_load_dwordx4 v[34:37], v[16:17], off offset:-1024
	global_load_dwordx4 v[38:41], v[16:17], off
	s_waitcnt vmcnt(0)
	s_branch .Lfn_A1
.Lfn_A0:
	s_waitcnt vmcnt(4)
.Lfn_A1:
	s_add_i32 s4, s4, s0
	s_cmp_lt_i32 s4, 0x8000
	s_cselect_b32 s5, 1, 0
	s_cbranch_scc0 .Lfn_A2
	v_lshl_add_u64 v[76:77], v[16:17], 0, s[2:3]
	global_load_dwordx4 v[60:63], v[76:77], off offset:-3072
	global_load_dwordx4 v[64:67], v[76:77], off offset:-2048
	global_load_dwordx4 v[68:71], v[76:77], off offset:-1024
	global_load_dwordx4 v[72:75], v[76:77], off
.Lfn_A2:
	v_pk_mul_f32 v[42:43], v[26:27], v[26:27]
	v_pk_mul_f32 v[44:45], v[34:35], v[34:35]
	v_pk_fma_f32 v[42:43], v[28:29], v[28:29], v[42:43]
	v_pk_fma_f32 v[44:45], v[36:37], v[36:37], v[44:45]
	v_pk_fma_f32 v[42:43], v[30:31], v[30:31], v[42:43]
	v_pk_fma_f32 v[44:45], v[38:39], v[38:39], v[44:45]
	v_pk_fma_f32 v[42:43], v[32:33], v[32:33], v[42:43]
	v_pk_fma_f32 v[44:45], v[40:41], v[40:41], v[44:45]
	v_pk_add_f32 v[42:43], v[42:43], v[44:45]
	s_nop 0
	v_add_f32_e32 v25, v42, v43
	s_nop 1
	v_add_f32_dpp v25, v25, v25 quad_perm:[1,0,3,2] row_mask:0xf bank_mask:0xf bound_ctrl:1
	s_nop 1
	v_add_f32_dpp v25, v25, v25 quad_perm:[2,3,0,1] row_mask:0xf bank_mask:0xf bound_ctrl:1
	s_nop 1
	v_add_f32_dpp v25, v25, v25 row_ror:4 row_mask:0xf bank_mask:0xf bound_ctrl:1
	s_nop 1
	v_add_f32_dpp v25, v25, v25 row_ror:8 row_mask:0xf bank_mask:0xf bound_ctrl:1
	v_mov_b32_e32 v46, v25
	v_mov_b32_e32 v47, v25
	s_nop 1
	v_permlane16_swap_b32_e32 v46, v47
	v_add_f32_e32 v25, v46, v47
	v_mov_b32_e32 v46, v25
	v_mov_b32_e32 v47, v25
	s_nop 1
	v_permlane32_swap_b32_e32 v46, v47
	v_add_f32_e32 v25, v46, v47
	v_fmamk_f32 v25, v25, 0x3a800000, v24
	v_rsq_f32_e32 v42, v25
	s_nop 0
	v_pk_mul_f32 v[26:27], v[26:27], v[42:43] op_sel_hi:[1,0]
	v_pk_mul_f32 v[28:29], v[28:29], v[42:43] op_sel_hi:[1,0]
	v_pk_mul_f32 v[30:31], v[30:31], v[42:43] op_sel_hi:[1,0]
	v_pk_mul_f32 v[32:33], v[32:33], v[42:43] op_sel_hi:[1,0]
	v_pk_mul_f32 v[34:35], v[34:35], v[42:43] op_sel_hi:[1,0]
	v_pk_mul_f32 v[36:37], v[36:37], v[42:43] op_sel_hi:[1,0]
	v_pk_mul_f32 v[38:39], v[38:39], v[42:43] op_sel_hi:[1,0]
	v_pk_mul_f32 v[40:41], v[40:41], v[42:43] op_sel_hi:[1,0]
	v_pk_mul_f32 v[26:27], v[0:1], v[26:27]
	v_pk_mul_f32 v[28:29], v[2:3], v[28:29]
	v_pk_mul_f32 v[30:31], v[4:5], v[30:31]
	v_pk_mul_f32 v[32:33], v[6:7], v[32:33]
	v_pk_mul_f32 v[34:35], v[8:9], v[34:35]
	v_pk_mul_f32 v[36:37], v[10:11], v[36:37]
	v_pk_mul_f32 v[38:39], v[12:13], v[38:39]
	v_pk_mul_f32 v[40:41], v[14:15], v[40:41]
	global_store_dwordx4 v[16:17], v[26:29], off offset:-3072
	global_store_dwordx4 v[16:17], v[30:33], off offset:-2048
	global_store_dwordx4 v[16:17], v[34:37], off offset:-1024
	global_store_dwordx4 v[16:17], v[38:41], off
	s_cmp_lg_u32 s5, 0
	s_cbranch_scc0 .LBB0_1747
	s_waitcnt vmcnt(4)
	s_add_i32 s4, s4, s0
	s_cmp_lt_i32 s4, 0x8000
	s_cselect_b32 s5, 1, 0
	s_cbranch_scc0 .Lfn_B2
	v_lshl_add_u64 v[16:17], v[76:77], 0, s[2:3]
	global_load_dwordx4 v[26:29], v[16:17], off offset:-3072
	global_load_dwordx4 v[30:33], v[16:17], off offset:-2048
	global_load_dwordx4 v[34:37], v[16:17], off offset:-1024
	global_load_dwordx4 v[38:41], v[16:17], off
.Lfn_B2:
	v_pk_mul_f32 v[42:43], v[60:61], v[60:61]
	v_pk_mul_f32 v[44:45], v[68:69], v[68:69]
	v_pk_fma_f32 v[42:43], v[62:63], v[62:63], v[42:43]
	v_pk_fma_f32 v[44:45], v[70:71], v[70:71], v[44:45]
	v_pk_fma_f32 v[42:43], v[64:65], v[64:65], v[42:43]
	v_pk_fma_f32 v[44:45], v[72:73], v[72:73], v[44:45]
	v_pk_fma_f32 v[42:43], v[66:67], v[66:67], v[42:43]
	v_pk_fma_f32 v[44:45], v[74:75], v[74:75], v[44:45]
	v_pk_add_f32 v[42:43], v[42:43], v[44:45]
	s_nop 0
	v_add_f32_e32 v25, v42, v43
	s_nop 1
	v_add_f32_dpp v25, v25, v25 quad_perm:[1,0,3,2] row_mask:0xf bank_mask:0xf bound_ctrl:1
	s_nop 1
	v_add_f32_dpp v25, v25, v25 quad_perm:[2,3,0,1] row_mask:0xf bank_mask:0xf bound_ctrl:1
	s_nop 1
	v_add_f32_dpp v25, v25, v25 row_ror:4 row_mask:0xf bank_mask:0xf bound_ctrl:1
	s_nop 1
	v_add_f32_dpp v25, v25, v25 row_ror:8 row_mask:0xf bank_mask:0xf bound_ctrl:1
	v_mov_b32_e32 v46, v25
	v_mov_b32_e32 v47, v25
	s_nop 1
	v_permlane16_swap_b32_e32 v46, v47
	v_add_f32_e32 v25, v46, v47
	v_mov_b32_e32 v46, v25
	v_mov_b32_e32 v47, v25
	s_nop 1
	v_permlane32_swap_b32_e32 v46, v47
	v_add_f32_e32 v25, v46, v47
	v_fmamk_f32 v25, v25, 0x3a800000, v24
	v_rsq_f32_e32 v42, v25
	s_nop 0
	v_pk_mul_f32 v[60:61], v[60:61], v[42:43] op_sel_hi:[1,0]
	v_pk_mul_f32 v[62:63], v[62:63], v[42:43] op_sel_hi:[1,0]
	v_pk_mul_f32 v[64:65], v[64:65], v[42:43] op_sel_hi:[1,0]
	v_pk_mul_f32 v[66:67], v[66:67], v[42:43] op_sel_hi:[1,0]
	v_pk_mul_f32 v[68:69], v[68:69], v[42:43] op_sel_hi:[1,0]
	v_pk_mul_f32 v[70:71], v[70:71], v[42:43] op_sel_hi:[1,0]
	v_pk_mul_f32 v[72:73], v[72:73], v[42:43] op_sel_hi:[1,0]
	v_pk_mul_f32 v[74:75], v[74:75], v[42:43] op_sel_hi:[1,0]
	v_pk_mul_f32 v[60:61], v[0:1], v[60:61]
	v_pk_mul_f32 v[62:63], v[2:3], v[62:63]
	v_pk_mul_f32 v[64:65], v[4:5], v[64:65]
	v_pk_mul_f32 v[66:67], v[6:7], v[66:67]
	v_pk_mul_f32 v[68:69], v[8:9], v[68:69]
	v_pk_mul_f32 v[70:71], v[10:11], v[70:71]
	v_pk_mul_f32 v[72:73], v[12:13], v[72:73]
	v_pk_mul_f32 v[74:75], v[14:15], v[74:75]
	global_store_dwordx4 v[76:77], v[60:63], off offset:-3072
	global_store_dwordx4 v[76:77], v[64:67], off offset:-2048
	global_store_dwordx4 v[76:77], v[68:71], off offset:-1024
	global_store_dwordx4 v[76:77], v[72:75], off
	s_cmp_lg_u32 s5, 0
	s_cbranch_scc1 .Lfn_A0
